# row_pass mode 2 (k=8) also software-pipelined, p-row load hoisted into the load group
# speedup vs baseline: 1.0110x; 1.0110x over previous
.LBB0_127:
	v_readlane_b32 s18, v252, 0
	v_readlane_b32 s20, v252, 51
	v_readlane_b32 s19, v252, 1
	v_readlane_b32 s21, v252, 52
	s_mov_b64 s[4:5], s[18:19]
	s_mov_b64 s[30:31], s[18:19]
	v_mov_b32_e32 v0, v162
	s_andn2_b64 vcc, exec, s[20:21]
	s_cbranch_vccnz .LBB0_150
	s_xor_b64 s[20:21], s[6:7], -1
	v_readlane_b32 s29, v251, 62
	s_cmp_lg_u32 s29, 11
	s_cselect_b64 s[34:35], -1, 0
	s_cmp_eq_u32 s29, 8
	s_cselect_b64 s[36:37], -1, 0
	s_and_b64 s[38:39], s[36:37], exec
	s_cselect_b32 s23, 38, 41
	s_cmp_lg_u32 s29, 5
	s_cselect_b32 s23, s23, 33
	s_lshl_b32 s23, s23, 3
	s_load_dwordx2 s[4:5], s[4:5], s23 offset:0x0
	s_nop 0
	s_load_dwordx2 s[40:41], s[30:31], 0x158
	s_xor_b64 s[30:31], s[64:65], -1
	s_or_b64 s[30:31], s[30:31], s[34:35]
	s_and_b64 s[34:35], s[64:65], exec
	s_cselect_b32 s23, 0x1000, 0
	s_waitcnt lgkmcnt(0)
	s_add_u32 s4, s4, s23
	s_load_dwordx4 s[60:63], s[18:19], 0x150
	v_lshlrev_b32_e32 v18, 2, v0
	s_addc_u32 s5, s5, 0
	v_ashrrev_i32_e32 v19, 31, v18
	s_and_b64 s[6:7], s[6:7], s[36:37]
	s_waitcnt vmcnt(0)
	v_lshlrev_b64 v[2:3], 2, v[18:19]
	s_xor_b64 s[34:35], s[6:7], -1
	v_lshl_add_u64 v[20:21], s[4:5], 0, v[2:3]
	s_and_b64 s[4:5], s[64:65], exec
	v_readlane_b32 s5, v251, 26
	s_cselect_b32 s23, 0x80000, 0
	s_cselect_b32 s4, 0x1000000, 0
	s_waitcnt lgkmcnt(0)
	s_add_u32 s36, s62, s5
	v_readlane_b32 s5, v251, 27
	s_addc_u32 s37, s63, s5
	v_readlane_b32 s38, v251, 45
	v_readlane_b32 s39, v251, 46
	s_add_u32 s29, s38, s4
	s_addc_u32 s59, s39, 0
	v_readlane_b32 s4, v251, 51
	v_readlane_b32 s5, v251, 52
	s_add_u32 s38, s62, s4
	s_addc_u32 s39, s63, s5
	s_add_u32 s40, s40, s4
	s_addc_u32 s41, s41, s5
	v_readlane_b32 s4, v251, 30
	v_readlane_b32 s5, v251, 31
	s_add_u32 s4, s60, s4
	s_addc_u32 s5, s61, s5
	v_readlane_b32 s42, v251, 49
	v_lshlrev_b64 v[22:23], 1, v[18:19]
	v_lshl_add_u64 v[24:25], s[4:5], 0, v[2:3]
	v_readlane_b32 s43, v251, 50
	s_and_b64 vcc, exec, s[30:31]
	s_cbranch_vccz .LBB0_131
	s_and_b64 vcc, exec, s[20:21]
	s_cbranch_vccnz .LBB0_131
	s_and_b64 vcc, exec, s[6:7]
	s_cbranch_vccnz .Lrq_entry
	s_branch .Lrp_entry

.Lrp_tail2:
	s_waitcnt vmcnt(0)
	s_waitcnt vmcnt(11)
	v_and_b32_e32 v117, 0xffff0000, v78
	v_lshlrev_b32_e32 v115, 16, v78
	s_waitcnt vmcnt(9)
	v_and_b32_e32 v116, 0xffff0000, v110
	v_lshlrev_b32_e32 v114, 16, v110
	v_lshlrev_b32_e32 v118, 16, v111
	v_and_b32_e32 v78, 0xffff0000, v111
	s_waitcnt vmcnt(8)
	v_lshlrev_b32_e32 v111, 16, v112
	v_lshlrev_b32_e32 v110, 16, v80
	v_and_b32_e32 v121, 0xffff0000, v112
	v_and_b32_e32 v120, 0xffff0000, v80
	v_lshlrev_b32_e32 v122, 16, v81
	v_and_b32_e32 v112, 0xffff0000, v81
	v_pk_mul_f32 v[80:81], v[116:117], v[116:117]
	v_lshlrev_b32_e32 v119, 16, v79
	v_pk_mul_f32 v[124:125], v[120:121], v[120:121]
	v_pk_fma_f32 v[80:81], v[114:115], v[114:115], v[80:81]
	v_and_b32_e32 v79, 0xffff0000, v79
	v_lshlrev_b32_e32 v123, 16, v113
	v_pk_fma_f32 v[124:125], v[110:111], v[110:111], v[124:125]
	v_pk_fma_f32 v[80:81], v[118:119], v[118:119], v[80:81]
	v_and_b32_e32 v113, 0xffff0000, v113
	v_pk_fma_f32 v[124:125], v[122:123], v[122:123], v[124:125]
	v_pk_fma_f32 v[80:81], v[78:79], v[78:79], v[80:81]
	v_pk_fma_f32 v[124:125], v[112:113], v[112:113], v[124:125]
	v_add_f32_e32 v64, v80, v81
	v_add_f32_e32 v64, v64, v124
	v_add_f32_e32 v64, v64, v125
	ds_bpermute_b32 v80, v163, v64
	v_mov_b32_e32 v125, v78
	v_mov_b32_e32 v124, v118
	v_mov_b32_e32 v126, v122
	v_mov_b32_e32 v127, v112
	s_waitcnt lgkmcnt(0)
	v_add_f32_e32 v64, v64, v80
	ds_bpermute_b32 v80, v164, v64
	v_mov_b32_e32 v112, v123
	s_waitcnt lgkmcnt(0)
	v_add_f32_e32 v64, v64, v80
	ds_bpermute_b32 v80, v165, v64
	s_waitcnt lgkmcnt(0)
	v_add_f32_e32 v64, v64, v80
	ds_bpermute_b32 v81, v166, v64
	v_mov_b32_e32 v80, v114
	s_waitcnt lgkmcnt(0)
	v_add_f32_e32 v64, v64, v81
	ds_bpermute_b32 v114, v167, v64
	v_mov_b32_e32 v81, v116
	v_mov_b32_e32 v116, v115
	v_mov_b32_e32 v115, v120
	v_mov_b32_e32 v120, v111
	s_waitcnt lgkmcnt(0)
	v_add_f32_e32 v64, v64, v114
	ds_bpermute_b32 v78, v168, v64
	v_mov_b32_e32 v114, v110
	s_waitcnt lgkmcnt(0)
	v_add_f32_e32 v64, v64, v78
	v_fmamk_f32 v64, v64, 0x3a800000, v169
	v_mul_f32_e32 v78, 0x4b800000, v64
	v_cmp_gt_f32_e32 vcc, s74, v64
	s_nop 1
	v_cndmask_b32_e32 v64, v64, v78, vcc
	v_rsq_f32_e32 v64, v64
	v_mov_b32_e32 v78, v119
	v_mul_f32_e32 v110, 0x45800000, v64
	v_cndmask_b32_e32 v64, v64, v110, vcc
	v_pk_mul_f32 v[110:111], v[80:81], v[64:65] op_sel_hi:[1,0]
	v_pk_mul_f32 v[80:81], v[124:125], v[64:65] op_sel_hi:[1,0]
	v_pk_mul_f32 v[116:117], v[116:117], v[64:65] op_sel_hi:[1,0]
	v_pk_mul_f32 v[118:119], v[78:79], v[64:65] op_sel_hi:[1,0]
	v_pk_mul_f32 v[114:115], v[114:115], v[64:65] op_sel_hi:[1,0]
	v_pk_mul_f32 v[122:123], v[126:127], v[64:65] op_sel_hi:[1,0]
	v_pk_mul_f32 v[120:121], v[120:121], v[64:65] op_sel_hi:[1,0]
	v_pk_mul_f32 v[112:113], v[112:113], v[64:65] op_sel_hi:[1,0]
	s_waitcnt vmcnt(5)
	v_pk_fma_f32 v[80:81], v[68:69], v[80:81], v[76:77]
	v_pk_fma_f32 v[78:79], v[66:67], v[110:111], v[74:75]
	s_waitcnt vmcnt(4)
	v_pk_fma_f32 v[76:77], v[72:73], v[118:119], v[92:93]
	v_pk_fma_f32 v[74:75], v[70:71], v[116:117], v[90:91]
	s_waitcnt vmcnt(1)
	v_pk_fma_f32 v[72:73], v[96:97], v[122:123], v[104:105]
	v_pk_fma_f32 v[70:71], v[94:95], v[114:115], v[102:103]
	s_waitcnt vmcnt(0)
	v_pk_fma_f32 v[68:69], v[100:101], v[112:113], v[108:109]
	v_pk_fma_f32 v[66:67], v[98:99], v[120:121], v[106:107]
	v_mov_b32_e32 v90, 1.0
	s_waitcnt vmcnt(3)
	v_pk_mul_f32 v[90:91], v[78:79], v[78:79]
	s_waitcnt vmcnt(2)
	v_pk_mul_f32 v[92:93], v[74:75], v[74:75]
	v_pk_mul_f32 v[94:95], v[80:81], v[80:81]
	v_pk_mul_f32 v[96:97], v[76:77], v[76:77]
	v_mov_b32_e32 v98, v95
	v_mov_b32_e32 v99, v97
	v_mov_b32_e32 v95, v96
	v_mov_b32_e32 v96, v90
	v_mov_b32_e32 v97, v92
	v_mov_b32_e32 v92, v91
	v_pk_add_f32 v[90:91], v[96:97], v[92:93]
	s_waitcnt vmcnt(0)
	v_mov_b32_e32 v96, v66
	v_pk_add_f32 v[90:91], v[94:95], v[90:91]
	v_mov_b32_e32 v97, v70
	v_pk_add_f32 v[90:91], v[98:99], v[90:91]
	v_mov_b32_e32 v98, v67
	v_mov_b32_e32 v99, v71
	v_pk_mul_f32 v[98:99], v[98:99], v[98:99]
	v_mov_b32_e32 v94, v68
	v_mov_b32_e32 v95, v72
	v_pk_fma_f32 v[96:97], v[96:97], v[96:97], v[98:99]
	v_mov_b32_e32 v92, v69
	v_mov_b32_e32 v93, v73
	v_pk_fma_f32 v[94:95], v[94:95], v[94:95], v[96:97]
	v_add_f32_e32 v64, v90, v91
	v_pk_fma_f32 v[92:93], v[92:93], v[92:93], v[94:95]
	s_nop 0
	v_add_f32_e32 v64, v93, v64
	v_add_f32_e32 v64, v92, v64
	ds_bpermute_b32 v90, v163, v64
	s_waitcnt lgkmcnt(0)
	v_add_f32_e32 v64, v64, v90
	ds_bpermute_b32 v90, v164, v64
	s_waitcnt lgkmcnt(0)
	v_add_f32_e32 v64, v64, v90
	ds_bpermute_b32 v90, v165, v64
	s_waitcnt lgkmcnt(0)
	v_add_f32_e32 v64, v64, v90
	ds_bpermute_b32 v90, v166, v64
	s_waitcnt lgkmcnt(0)
	v_add_f32_e32 v64, v64, v90
	ds_bpermute_b32 v90, v167, v64
	s_waitcnt lgkmcnt(0)
	v_add_f32_e32 v64, v64, v90
	ds_bpermute_b32 v90, v168, v64
	s_waitcnt lgkmcnt(0)
	v_add_f32_e32 v64, v64, v90
	v_fmamk_f32 v64, v64, 0x3a800000, v169
	v_mul_f32_e32 v90, 0x4b800000, v64
	v_cmp_gt_f32_e32 vcc, s74, v64
	s_nop 1
	v_cndmask_b32_e32 v64, v64, v90, vcc
	v_rsq_f32_e32 v64, v64
	s_nop 0
	v_mul_f32_e32 v90, 0x45800000, v64
	v_cndmask_b32_e32 v90, v64, v90, vcc
	v_mov_b32_e32 v92, v136
	v_mov_b32_e32 v93, v137
	v_mov_b32_e32 v91, v90
	s_waitcnt vmcnt(3)
	global_store_dwordx4 v[134:135], v[78:81], off offset:-3072 nt
	v_mov_b32_e32 v94, v90
	v_mov_b32_e32 v95, v90
	v_pk_mul_f32 v[80:81], v[80:81], v[94:95]
	v_pk_mul_f32 v[78:79], v[78:79], v[90:91]
	s_nop 0
	v_cvt_pk_bf16_f32 v78, v78, v79
	v_cvt_pk_bf16_f32 v79, v80, v81
	v_add_co_u32_e32 v80, vcc, 0x2b00000, v92
	s_nop 1
	v_addc_co_u32_e32 v81, vcc, 0, v93, vcc
	global_store_dwordx2 v[80:81], v[78:79], off
	s_waitcnt vmcnt(4)
	global_store_dwordx4 v[134:135], v[74:77], off offset:-2048 nt
	v_pk_mul_f32 v[78:79], v[76:77], v[94:95]
	v_pk_mul_f32 v[94:95], v[74:75], v[90:91]
	s_nop 0
	v_cvt_pk_bf16_f32 v94, v94, v95
	v_cvt_pk_bf16_f32 v95, v78, v79
	global_store_dwordx2 v[80:81], v[94:95], off offset:512
	s_waitcnt vmcnt(2)
	global_store_dwordx4 v[134:135], v[70:73], off offset:-1024 nt
	v_mov_b32_e32 v74, v90
	v_mov_b32_e32 v75, v90
	v_pk_mul_f32 v[72:73], v[72:73], v[74:75]
	v_pk_mul_f32 v[70:71], v[70:71], v[90:91]
	s_nop 0
	v_cvt_pk_bf16_f32 v70, v70, v71
	v_cvt_pk_bf16_f32 v71, v72, v73
	v_add_co_u32_e32 v72, vcc, 0x2b00000, v92
	s_nop 1
	v_addc_co_u32_e32 v73, vcc, 0, v93, vcc
	global_store_dwordx2 v[72:73], v[70:71], off offset:1024
	s_waitcnt vmcnt(3)
	global_store_dwordx4 v[134:135], v[66:69], off nt
	v_pk_mul_f32 v[70:71], v[68:69], v[74:75]
	v_pk_mul_f32 v[74:75], v[66:67], v[90:91]
	s_nop 0
	v_cvt_pk_bf16_f32 v74, v74, v75
	v_cvt_pk_bf16_f32 v75, v70, v71
	global_store_dwordx2 v[72:73], v[74:75], off offset:1536
	s_branch .LBB0_150
.Lrq_entry:
	s_load_dwordx2 s[100:101], s[18:19], 0x10
	s_load_dwordx2 s[44:45], s[18:19], 0x18
	s_waitcnt lgkmcnt(0)
	s_add_u32 s4, s100, s29
	s_addc_u32 s5, s101, s59
	s_add_i32 s72, s42, 0xffffc000
	s_lshl_b64 vcc, s[72:73], 10
	s_add_u32 vcc_lo, vcc_lo, s23
	s_addc_u32 vcc_hi, vcc_hi, 0
	s_add_u32 vcc_lo, vcc_lo, s44
	s_addc_u32 vcc_hi, vcc_hi, s45
	s_cmpk_gt_i32 s42, 0x3fff
	s_cselect_b32 s4, vcc_lo, s4
	s_cselect_b32 s5, vcc_hi, s5
	v_lshl_add_u64 v[154:155], v[18:19], 2, s[4:5]
	global_load_dwordx4 v[142:145], v[154:155], off
	v_lshl_add_u64 v[150:151], s[36:37], 0, v[22:23]
	v_lshl_add_u64 v[2:3], s[40:41], 0, v[22:23]
	v_add_co_u32_e32 v2, vcc, 0x4c00000, v2
	s_nop 1
	v_addc_co_u32_e32 v3, vcc, 0, v3, vcc
	global_load_dwordx2 v[14:15], v[2:3], off offset:512 nt
	global_load_dwordx2 v[16:17], v[2:3], off offset:1024 nt
	global_load_dwordx2 v[46:47], v[2:3], off nt
	global_load_dwordx2 v[48:49], v[2:3], off offset:1536 nt
	s_nop 0
	global_load_dwordx4 v[2:5], v[20:21], off
	global_load_dwordx4 v[6:9], v[20:21], off offset:1024
	global_load_dwordx4 v[10:13], v[24:25], off offset:-3072 nt
	global_load_dwordx4 v[26:29], v[24:25], off offset:-2048 nt
	global_load_dwordx4 v[30:33], v[20:21], off offset:2048
	global_load_dwordx4 v[34:37], v[20:21], off offset:3072
	global_load_dwordx4 v[38:41], v[24:25], off offset:-1024 nt
	global_load_dwordx4 v[42:45], v[24:25], off nt
	v_mov_b32_e32 v130, v24
	v_mov_b32_e32 v131, v25
	v_lshl_add_u64 v[132:133], s[38:39], 0, v[22:23]
	v_readlane_b32 s4, v251, 53
	v_readlane_b32 s5, v251, 54
	s_add_u32 s42, s42, s4
	s_addc_u32 s43, s43, s5
	v_readlane_b32 s4, v251, 43
	v_readlane_b32 s5, v251, 44
	s_add_u32 s36, s36, s4
	s_addc_u32 s37, s37, s5
	v_readlane_b32 s4, v251, 47
	v_readlane_b32 s5, v251, 48
	s_add_u32 s29, s29, s4
	s_addc_u32 s59, s59, s5
	s_add_u32 s38, s38, s56
	s_addc_u32 s39, s39, s57
	s_add_u32 s40, s40, s56
	v_readlane_b32 s4, v251, 55
	s_addc_u32 s41, s41, s57
	v_readlane_b32 s5, v251, 56
	s_cmpk_gt_i32 s42, 0x41ff
	s_cselect_b32 s98, 0, 1
	s_nop 0
	v_lshl_add_u64 v[24:25], v[24:25], 0, s[4:5]
	global_load_dword v129, v[20:21], off
	global_load_dword v129, v[20:21], off
	global_load_dword v129, v[20:21], off
	global_load_dword v129, v[20:21], off
	global_load_dword v129, v[20:21], off
	global_load_dword v129, v[20:21], off
	global_load_dword v129, v[20:21], off
	global_load_dword v129, v[20:21], off
	global_load_dword v129, v[20:21], off
.Lrq_loop:
	s_cmp_eq_u32 s98, 0
	s_cbranch_scc1 .Lrq_tail1
	s_add_u32 s4, s100, s29
	s_addc_u32 s5, s101, s59
	s_add_i32 s72, s42, 0xffffc000
	s_lshl_b64 vcc, s[72:73], 10
	s_add_u32 vcc_lo, vcc_lo, s23
	s_addc_u32 vcc_hi, vcc_hi, 0
	s_add_u32 vcc_lo, vcc_lo, s44
	s_addc_u32 vcc_hi, vcc_hi, s45
	s_cmpk_gt_i32 s42, 0x3fff
	s_cselect_b32 s4, vcc_lo, s4
	s_cselect_b32 s5, vcc_hi, s5
	v_lshl_add_u64 v[154:155], v[18:19], 2, s[4:5]
	global_load_dwordx4 v[146:149], v[154:155], off
	v_lshl_add_u64 v[152:153], s[36:37], 0, v[22:23]
	v_lshl_add_u64 v[66:67], s[40:41], 0, v[22:23]
	v_add_co_u32_e32 v66, vcc, 0x4c00000, v66
	s_nop 1
	v_addc_co_u32_e32 v67, vcc, 0, v67, vcc
	global_load_dwordx2 v[78:79], v[66:67], off offset:512 nt
	global_load_dwordx2 v[80:81], v[66:67], off offset:1024 nt
	global_load_dwordx2 v[110:111], v[66:67], off nt
	global_load_dwordx2 v[112:113], v[66:67], off offset:1536 nt
	s_nop 0
	global_load_dwordx4 v[66:69], v[20:21], off
	global_load_dwordx4 v[70:73], v[20:21], off offset:1024
	global_load_dwordx4 v[74:77], v[24:25], off offset:-3072 nt
	global_load_dwordx4 v[90:93], v[24:25], off offset:-2048 nt
	global_load_dwordx4 v[94:97], v[20:21], off offset:2048
	global_load_dwordx4 v[98:101], v[20:21], off offset:3072
	global_load_dwordx4 v[102:105], v[24:25], off offset:-1024 nt
	global_load_dwordx4 v[106:109], v[24:25], off nt
	v_mov_b32_e32 v134, v24
	v_mov_b32_e32 v135, v25
	v_lshl_add_u64 v[136:137], s[38:39], 0, v[22:23]
	v_readlane_b32 s4, v251, 53
	v_readlane_b32 s5, v251, 54
	s_add_u32 s42, s42, s4
	s_addc_u32 s43, s43, s5
	v_readlane_b32 s4, v251, 43
	v_readlane_b32 s5, v251, 44
	s_add_u32 s36, s36, s4
	s_addc_u32 s37, s37, s5
	v_readlane_b32 s4, v251, 47
	v_readlane_b32 s5, v251, 48
	s_add_u32 s29, s29, s4
	s_addc_u32 s59, s59, s5
	s_add_u32 s38, s38, s56
	s_addc_u32 s39, s39, s57
	s_add_u32 s40, s40, s56
	v_readlane_b32 s4, v251, 55
	s_addc_u32 s41, s41, s57
	v_readlane_b32 s5, v251, 56
	s_cmpk_gt_i32 s42, 0x41ff
	s_cselect_b32 s98, 0, 1
	s_nop 0
	v_lshl_add_u64 v[24:25], v[24:25], 0, s[4:5]
	s_waitcnt vmcnt(33)
	v_and_b32_e32 v53, 0xffff0000, v14
	v_lshlrev_b32_e32 v51, 16, v14
	s_waitcnt vmcnt(31)
	v_and_b32_e32 v52, 0xffff0000, v46
	v_lshlrev_b32_e32 v50, 16, v46
	v_lshlrev_b32_e32 v54, 16, v47
	v_and_b32_e32 v14, 0xffff0000, v47
	s_waitcnt vmcnt(30)
	v_lshlrev_b32_e32 v47, 16, v48
	v_lshlrev_b32_e32 v46, 16, v16
	v_and_b32_e32 v57, 0xffff0000, v48
	v_and_b32_e32 v56, 0xffff0000, v16
	v_lshlrev_b32_e32 v58, 16, v17
	v_and_b32_e32 v48, 0xffff0000, v17
	v_pk_mul_f32 v[16:17], v[52:53], v[52:53]
	v_lshlrev_b32_e32 v55, 16, v15
	v_pk_mul_f32 v[60:61], v[56:57], v[56:57]
	v_pk_fma_f32 v[16:17], v[50:51], v[50:51], v[16:17]
	v_and_b32_e32 v15, 0xffff0000, v15
	v_lshlrev_b32_e32 v59, 16, v49
	v_pk_fma_f32 v[60:61], v[46:47], v[46:47], v[60:61]
	v_pk_fma_f32 v[16:17], v[54:55], v[54:55], v[16:17]
	v_and_b32_e32 v49, 0xffff0000, v49
	v_pk_fma_f32 v[60:61], v[58:59], v[58:59], v[60:61]
	v_pk_fma_f32 v[16:17], v[14:15], v[14:15], v[16:17]
	v_pk_fma_f32 v[60:61], v[48:49], v[48:49], v[60:61]
	v_add_f32_e32 v0, v16, v17
	v_add_f32_e32 v0, v0, v60
	v_add_f32_e32 v0, v0, v61
	ds_bpermute_b32 v16, v163, v0
	v_mov_b32_e32 v61, v14
	v_mov_b32_e32 v60, v54
	v_mov_b32_e32 v62, v58
	v_mov_b32_e32 v63, v48
	s_waitcnt lgkmcnt(0)
	v_add_f32_e32 v0, v0, v16
	ds_bpermute_b32 v16, v164, v0
	v_mov_b32_e32 v48, v59
	s_waitcnt lgkmcnt(0)
	v_add_f32_e32 v0, v0, v16
	ds_bpermute_b32 v16, v165, v0
	s_waitcnt lgkmcnt(0)
	v_add_f32_e32 v0, v0, v16
	ds_bpermute_b32 v17, v166, v0
	v_mov_b32_e32 v16, v50
	s_waitcnt lgkmcnt(0)
	v_add_f32_e32 v0, v0, v17
	ds_bpermute_b32 v50, v167, v0
	v_mov_b32_e32 v17, v52
	v_mov_b32_e32 v52, v51
	v_mov_b32_e32 v51, v56
	v_mov_b32_e32 v56, v47
	s_waitcnt lgkmcnt(0)
	v_add_f32_e32 v0, v0, v50
	ds_bpermute_b32 v14, v168, v0
	v_mov_b32_e32 v50, v46
	s_waitcnt lgkmcnt(0)
	v_add_f32_e32 v0, v0, v14
	v_fmamk_f32 v0, v0, 0x3a800000, v169
	v_mul_f32_e32 v14, 0x4b800000, v0
	v_cmp_gt_f32_e32 vcc, s74, v0
	s_nop 1
	v_cndmask_b32_e32 v0, v0, v14, vcc
	v_rsq_f32_e32 v0, v0
	v_mov_b32_e32 v14, v55
	v_mul_f32_e32 v46, 0x45800000, v0
	v_cndmask_b32_e32 v0, v0, v46, vcc
	v_pk_mul_f32 v[46:47], v[16:17], v[0:1] op_sel_hi:[1,0]
	v_pk_mul_f32 v[16:17], v[60:61], v[0:1] op_sel_hi:[1,0]
	v_pk_mul_f32 v[52:53], v[52:53], v[0:1] op_sel_hi:[1,0]
	v_pk_mul_f32 v[54:55], v[14:15], v[0:1] op_sel_hi:[1,0]
	v_pk_mul_f32 v[50:51], v[50:51], v[0:1] op_sel_hi:[1,0]
	v_pk_mul_f32 v[58:59], v[62:63], v[0:1] op_sel_hi:[1,0]
	v_pk_mul_f32 v[56:57], v[56:57], v[0:1] op_sel_hi:[1,0]
	v_pk_mul_f32 v[48:49], v[48:49], v[0:1] op_sel_hi:[1,0]
	s_waitcnt vmcnt(27)
	v_pk_fma_f32 v[16:17], v[4:5], v[16:17], v[12:13]
	v_pk_fma_f32 v[14:15], v[2:3], v[46:47], v[10:11]
	s_waitcnt vmcnt(26)
	v_pk_fma_f32 v[12:13], v[8:9], v[54:55], v[28:29]
	v_pk_fma_f32 v[10:11], v[6:7], v[52:53], v[26:27]
	s_waitcnt vmcnt(23)
	v_pk_fma_f32 v[8:9], v[32:33], v[58:59], v[40:41]
	v_pk_fma_f32 v[6:7], v[30:31], v[50:51], v[38:39]
	s_waitcnt vmcnt(22)
	v_pk_fma_f32 v[4:5], v[36:37], v[48:49], v[44:45]
	v_pk_fma_f32 v[2:3], v[34:35], v[56:57], v[42:43]
	v_mov_b32_e32 v26, 1.0
	v_mov_b32_e32 v28, v132
	v_mov_b32_e32 v29, v133
	v_mov_b32_e32 v27, v26
	s_waitcnt vmcnt(25)
	global_store_dwordx4 v[130:131], v[14:17], off offset:-3072 nt
	v_mov_b32_e32 v30, v26
	v_mov_b32_e32 v31, v26
	v_pk_mul_f32 v[16:17], v[16:17], v[30:31]
	v_pk_mul_f32 v[14:15], v[14:15], v[26:27]
	s_nop 0
	v_cvt_pk_bf16_f32 v14, v14, v15
	v_cvt_pk_bf16_f32 v15, v16, v17
	v_add_co_u32_e32 v16, vcc, 0x2b00000, v28
	s_nop 1
	v_addc_co_u32_e32 v17, vcc, 0, v29, vcc
	global_store_dwordx2 v[16:17], v[14:15], off
	s_waitcnt vmcnt(26)
	global_store_dwordx4 v[130:131], v[10:13], off offset:-2048 nt
	v_pk_mul_f32 v[14:15], v[12:13], v[30:31]
	v_pk_mul_f32 v[30:31], v[10:11], v[26:27]
	s_nop 0
	v_cvt_pk_bf16_f32 v30, v30, v31
	v_cvt_pk_bf16_f32 v31, v14, v15
	global_store_dwordx2 v[16:17], v[30:31], off offset:512
	s_waitcnt vmcnt(24)
	global_store_dwordx4 v[130:131], v[6:9], off offset:-1024 nt
	v_mov_b32_e32 v10, v26
	v_mov_b32_e32 v11, v26
	v_pk_mul_f32 v[8:9], v[8:9], v[10:11]
	v_pk_mul_f32 v[6:7], v[6:7], v[26:27]
	s_nop 0
	v_cvt_pk_bf16_f32 v6, v6, v7
	v_cvt_pk_bf16_f32 v7, v8, v9
	v_add_co_u32_e32 v8, vcc, 0x2b00000, v28
	s_nop 1
	v_addc_co_u32_e32 v9, vcc, 0, v29, vcc
	global_store_dwordx2 v[8:9], v[6:7], off offset:1024
	s_waitcnt vmcnt(25)
	global_store_dwordx4 v[130:131], v[2:5], off nt
	v_pk_mul_f32 v[6:7], v[4:5], v[10:11]
	v_pk_mul_f32 v[10:11], v[2:3], v[26:27]
	s_nop 0
	v_cvt_pk_bf16_f32 v10, v10, v11
	v_cvt_pk_bf16_f32 v11, v6, v7
	global_store_dwordx2 v[8:9], v[10:11], off offset:1536
	v_cvt_pk_bf16_f32 v142, v142, v143
	v_cvt_pk_bf16_f32 v143, v144, v145
	global_store_dwordx2 v[150:151], v[142:143], off
	s_cmp_eq_u32 s98, 0
	s_cbranch_scc1 .Lrq_tail2
	s_add_u32 s4, s100, s29
	s_addc_u32 s5, s101, s59
	s_add_i32 s72, s42, 0xffffc000
	s_lshl_b64 vcc, s[72:73], 10
	s_add_u32 vcc_lo, vcc_lo, s23
	s_addc_u32 vcc_hi, vcc_hi, 0
	s_add_u32 vcc_lo, vcc_lo, s44
	s_addc_u32 vcc_hi, vcc_hi, s45
	s_cmpk_gt_i32 s42, 0x3fff
	s_cselect_b32 s4, vcc_lo, s4
	s_cselect_b32 s5, vcc_hi, s5
	v_lshl_add_u64 v[154:155], v[18:19], 2, s[4:5]
	global_load_dwordx4 v[142:145], v[154:155], off
	v_lshl_add_u64 v[150:151], s[36:37], 0, v[22:23]
	v_lshl_add_u64 v[2:3], s[40:41], 0, v[22:23]
	v_add_co_u32_e32 v2, vcc, 0x4c00000, v2
	s_nop 1
	v_addc_co_u32_e32 v3, vcc, 0, v3, vcc
	global_load_dwordx2 v[14:15], v[2:3], off offset:512 nt
	global_load_dwordx2 v[16:17], v[2:3], off offset:1024 nt
	global_load_dwordx2 v[46:47], v[2:3], off nt
	global_load_dwordx2 v[48:49], v[2:3], off offset:1536 nt
	s_nop 0
	global_load_dwordx4 v[2:5], v[20:21], off
	global_load_dwordx4 v[6:9], v[20:21], off offset:1024
	global_load_dwordx4 v[10:13], v[24:25], off offset:-3072 nt
	global_load_dwordx4 v[26:29], v[24:25], off offset:-2048 nt
	global_load_dwordx4 v[30:33], v[20:21], off offset:2048
	global_load_dwordx4 v[34:37], v[20:21], off offset:3072
	global_load_dwordx4 v[38:41], v[24:25], off offset:-1024 nt
	global_load_dwordx4 v[42:45], v[24:25], off nt
	v_mov_b32_e32 v130, v24
	v_mov_b32_e32 v131, v25
	v_lshl_add_u64 v[132:133], s[38:39], 0, v[22:23]
	v_readlane_b32 s4, v251, 53
	v_readlane_b32 s5, v251, 54
	s_add_u32 s42, s42, s4
	s_addc_u32 s43, s43, s5
	v_readlane_b32 s4, v251, 43
	v_readlane_b32 s5, v251, 44
	s_add_u32 s36, s36, s4
	s_addc_u32 s37, s37, s5
	v_readlane_b32 s4, v251, 47
	v_readlane_b32 s5, v251, 48
	s_add_u32 s29, s29, s4
	s_addc_u32 s59, s59, s5
	s_add_u32 s38, s38, s56
	s_addc_u32 s39, s39, s57
	s_add_u32 s40, s40, s56
	v_readlane_b32 s4, v251, 55
	s_addc_u32 s41, s41, s57
	v_readlane_b32 s5, v251, 56
	s_cmpk_gt_i32 s42, 0x41ff
	s_cselect_b32 s98, 0, 1
	s_nop 0
	v_lshl_add_u64 v[24:25], v[24:25], 0, s[4:5]
	s_waitcnt vmcnt(33)
	v_and_b32_e32 v117, 0xffff0000, v78
	v_lshlrev_b32_e32 v115, 16, v78
	s_waitcnt vmcnt(31)
	v_and_b32_e32 v116, 0xffff0000, v110
	v_lshlrev_b32_e32 v114, 16, v110
	v_lshlrev_b32_e32 v118, 16, v111
	v_and_b32_e32 v78, 0xffff0000, v111
	s_waitcnt vmcnt(30)
	v_lshlrev_b32_e32 v111, 16, v112
	v_lshlrev_b32_e32 v110, 16, v80
	v_and_b32_e32 v121, 0xffff0000, v112
	v_and_b32_e32 v120, 0xffff0000, v80
	v_lshlrev_b32_e32 v122, 16, v81
	v_and_b32_e32 v112, 0xffff0000, v81
	v_pk_mul_f32 v[80:81], v[116:117], v[116:117]
	v_lshlrev_b32_e32 v119, 16, v79
	v_pk_mul_f32 v[124:125], v[120:121], v[120:121]
	v_pk_fma_f32 v[80:81], v[114:115], v[114:115], v[80:81]
	v_and_b32_e32 v79, 0xffff0000, v79
	v_lshlrev_b32_e32 v123, 16, v113
	v_pk_fma_f32 v[124:125], v[110:111], v[110:111], v[124:125]
	v_pk_fma_f32 v[80:81], v[118:119], v[118:119], v[80:81]
	v_and_b32_e32 v113, 0xffff0000, v113
	v_pk_fma_f32 v[124:125], v[122:123], v[122:123], v[124:125]
	v_pk_fma_f32 v[80:81], v[78:79], v[78:79], v[80:81]
	v_pk_fma_f32 v[124:125], v[112:113], v[112:113], v[124:125]
	v_add_f32_e32 v64, v80, v81
	v_add_f32_e32 v64, v64, v124
	v_add_f32_e32 v64, v64, v125
	ds_bpermute_b32 v80, v163, v64
	v_mov_b32_e32 v125, v78
	v_mov_b32_e32 v124, v118
	v_mov_b32_e32 v126, v122
	v_mov_b32_e32 v127, v112
	s_waitcnt lgkmcnt(0)
	v_add_f32_e32 v64, v64, v80
	ds_bpermute_b32 v80, v164, v64
	v_mov_b32_e32 v112, v123
	s_waitcnt lgkmcnt(0)
	v_add_f32_e32 v64, v64, v80
	ds_bpermute_b32 v80, v165, v64
	s_waitcnt lgkmcnt(0)
	v_add_f32_e32 v64, v64, v80
	ds_bpermute_b32 v81, v166, v64
	v_mov_b32_e32 v80, v114
	s_waitcnt lgkmcnt(0)
	v_add_f32_e32 v64, v64, v81
	ds_bpermute_b32 v114, v167, v64
	v_mov_b32_e32 v81, v116
	v_mov_b32_e32 v116, v115
	v_mov_b32_e32 v115, v120
	v_mov_b32_e32 v120, v111
	s_waitcnt lgkmcnt(0)
	v_add_f32_e32 v64, v64, v114
	ds_bpermute_b32 v78, v168, v64
	v_mov_b32_e32 v114, v110
	s_waitcnt lgkmcnt(0)
	v_add_f32_e32 v64, v64, v78
	v_fmamk_f32 v64, v64, 0x3a800000, v169
	v_mul_f32_e32 v78, 0x4b800000, v64
	v_cmp_gt_f32_e32 vcc, s74, v64
	s_nop 1
	v_cndmask_b32_e32 v64, v64, v78, vcc
	v_rsq_f32_e32 v64, v64
	v_mov_b32_e32 v78, v119
	v_mul_f32_e32 v110, 0x45800000, v64
	v_cndmask_b32_e32 v64, v64, v110, vcc
	v_pk_mul_f32 v[110:111], v[80:81], v[64:65] op_sel_hi:[1,0]
	v_pk_mul_f32 v[80:81], v[124:125], v[64:65] op_sel_hi:[1,0]
	v_pk_mul_f32 v[116:117], v[116:117], v[64:65] op_sel_hi:[1,0]
	v_pk_mul_f32 v[118:119], v[78:79], v[64:65] op_sel_hi:[1,0]
	v_pk_mul_f32 v[114:115], v[114:115], v[64:65] op_sel_hi:[1,0]
	v_pk_mul_f32 v[122:123], v[126:127], v[64:65] op_sel_hi:[1,0]
	v_pk_mul_f32 v[120:121], v[120:121], v[64:65] op_sel_hi:[1,0]
	v_pk_mul_f32 v[112:113], v[112:113], v[64:65] op_sel_hi:[1,0]
	s_waitcnt vmcnt(27)
	v_pk_fma_f32 v[80:81], v[68:69], v[80:81], v[76:77]
	v_pk_fma_f32 v[78:79], v[66:67], v[110:111], v[74:75]
	s_waitcnt vmcnt(26)
	v_pk_fma_f32 v[76:77], v[72:73], v[118:119], v[92:93]
	v_pk_fma_f32 v[74:75], v[70:71], v[116:117], v[90:91]
	s_waitcnt vmcnt(23)
	v_pk_fma_f32 v[72:73], v[96:97], v[122:123], v[104:105]
	v_pk_fma_f32 v[70:71], v[94:95], v[114:115], v[102:103]
	s_waitcnt vmcnt(22)
	v_pk_fma_f32 v[68:69], v[100:101], v[112:113], v[108:109]
	v_pk_fma_f32 v[66:67], v[98:99], v[120:121], v[106:107]
	v_mov_b32_e32 v90, 1.0
	v_mov_b32_e32 v92, v136
	v_mov_b32_e32 v93, v137
	v_mov_b32_e32 v91, v90
	s_waitcnt vmcnt(25)
	global_store_dwordx4 v[134:135], v[78:81], off offset:-3072 nt
	v_mov_b32_e32 v94, v90
	v_mov_b32_e32 v95, v90
	v_pk_mul_f32 v[80:81], v[80:81], v[94:95]
	v_pk_mul_f32 v[78:79], v[78:79], v[90:91]
	s_nop 0
	v_cvt_pk_bf16_f32 v78, v78, v79
	v_cvt_pk_bf16_f32 v79, v80, v81
	v_add_co_u32_e32 v80, vcc, 0x2b00000, v92
	s_nop 1
	v_addc_co_u32_e32 v81, vcc, 0, v93, vcc
	global_store_dwordx2 v[80:81], v[78:79], off
	s_waitcnt vmcnt(26)
	global_store_dwordx4 v[134:135], v[74:77], off offset:-2048 nt
	v_pk_mul_f32 v[78:79], v[76:77], v[94:95]
	v_pk_mul_f32 v[94:95], v[74:75], v[90:91]
	s_nop 0
	v_cvt_pk_bf16_f32 v94, v94, v95
	v_cvt_pk_bf16_f32 v95, v78, v79
	global_store_dwordx2 v[80:81], v[94:95], off offset:512
	s_waitcnt vmcnt(24)
	global_store_dwordx4 v[134:135], v[70:73], off offset:-1024 nt
	v_mov_b32_e32 v74, v90
	v_mov_b32_e32 v75, v90
	v_pk_mul_f32 v[72:73], v[72:73], v[74:75]
	v_pk_mul_f32 v[70:71], v[70:71], v[90:91]
	s_nop 0
	v_cvt_pk_bf16_f32 v70, v70, v71
	v_cvt_pk_bf16_f32 v71, v72, v73
	v_add_co_u32_e32 v72, vcc, 0x2b00000, v92
	s_nop 1
	v_addc_co_u32_e32 v73, vcc, 0, v93, vcc
	global_store_dwordx2 v[72:73], v[70:71], off offset:1024
	s_waitcnt vmcnt(25)
	global_store_dwordx4 v[134:135], v[66:69], off nt
	v_pk_mul_f32 v[70:71], v[68:69], v[74:75]
	v_pk_mul_f32 v[74:75], v[66:67], v[90:91]
	s_nop 0
	v_cvt_pk_bf16_f32 v74, v74, v75
	v_cvt_pk_bf16_f32 v75, v70, v71
	global_store_dwordx2 v[72:73], v[74:75], off offset:1536
	v_cvt_pk_bf16_f32 v146, v146, v147
	v_cvt_pk_bf16_f32 v147, v148, v149
	global_store_dwordx2 v[152:153], v[146:147], off
	s_branch .Lrq_loop
.Lrq_tail1:
	s_waitcnt vmcnt(0)
	s_waitcnt vmcnt(11)
	v_and_b32_e32 v53, 0xffff0000, v14
	v_lshlrev_b32_e32 v51, 16, v14
	s_waitcnt vmcnt(9)
	v_and_b32_e32 v52, 0xffff0000, v46
	v_lshlrev_b32_e32 v50, 16, v46
	v_lshlrev_b32_e32 v54, 16, v47
	v_and_b32_e32 v14, 0xffff0000, v47
	s_waitcnt vmcnt(8)
	v_lshlrev_b32_e32 v47, 16, v48
	v_lshlrev_b32_e32 v46, 16, v16
	v_and_b32_e32 v57, 0xffff0000, v48
	v_and_b32_e32 v56, 0xffff0000, v16
	v_lshlrev_b32_e32 v58, 16, v17
	v_and_b32_e32 v48, 0xffff0000, v17
	v_pk_mul_f32 v[16:17], v[52:53], v[52:53]
	v_lshlrev_b32_e32 v55, 16, v15
	v_pk_mul_f32 v[60:61], v[56:57], v[56:57]
	v_pk_fma_f32 v[16:17], v[50:51], v[50:51], v[16:17]
	v_and_b32_e32 v15, 0xffff0000, v15
	v_lshlrev_b32_e32 v59, 16, v49
	v_pk_fma_f32 v[60:61], v[46:47], v[46:47], v[60:61]
	v_pk_fma_f32 v[16:17], v[54:55], v[54:55], v[16:17]
	v_and_b32_e32 v49, 0xffff0000, v49
	v_pk_fma_f32 v[60:61], v[58:59], v[58:59], v[60:61]
	v_pk_fma_f32 v[16:17], v[14:15], v[14:15], v[16:17]
	v_pk_fma_f32 v[60:61], v[48:49], v[48:49], v[60:61]
	v_add_f32_e32 v0, v16, v17
	v_add_f32_e32 v0, v0, v60
	v_add_f32_e32 v0, v0, v61
	ds_bpermute_b32 v16, v163, v0
	v_mov_b32_e32 v61, v14
	v_mov_b32_e32 v60, v54
	v_mov_b32_e32 v62, v58
	v_mov_b32_e32 v63, v48
	s_waitcnt lgkmcnt(0)
	v_add_f32_e32 v0, v0, v16
	ds_bpermute_b32 v16, v164, v0
	v_mov_b32_e32 v48, v59
	s_waitcnt lgkmcnt(0)
	v_add_f32_e32 v0, v0, v16
	ds_bpermute_b32 v16, v165, v0
	s_waitcnt lgkmcnt(0)
	v_add_f32_e32 v0, v0, v16
	ds_bpermute_b32 v17, v166, v0
	v_mov_b32_e32 v16, v50
	s_waitcnt lgkmcnt(0)
	v_add_f32_e32 v0, v0, v17
	ds_bpermute_b32 v50, v167, v0
	v_mov_b32_e32 v17, v52
	v_mov_b32_e32 v52, v51
	v_mov_b32_e32 v51, v56
	v_mov_b32_e32 v56, v47
	s_waitcnt lgkmcnt(0)
	v_add_f32_e32 v0, v0, v50
	ds_bpermute_b32 v14, v168, v0
	v_mov_b32_e32 v50, v46
	s_waitcnt lgkmcnt(0)
	v_add_f32_e32 v0, v0, v14
	v_fmamk_f32 v0, v0, 0x3a800000, v169
	v_mul_f32_e32 v14, 0x4b800000, v0
	v_cmp_gt_f32_e32 vcc, s74, v0
	s_nop 1
	v_cndmask_b32_e32 v0, v0, v14, vcc
	v_rsq_f32_e32 v0, v0
	v_mov_b32_e32 v14, v55
	v_mul_f32_e32 v46, 0x45800000, v0
	v_cndmask_b32_e32 v0, v0, v46, vcc
	v_pk_mul_f32 v[46:47], v[16:17], v[0:1] op_sel_hi:[1,0]
	v_pk_mul_f32 v[16:17], v[60:61], v[0:1] op_sel_hi:[1,0]
	v_pk_mul_f32 v[52:53], v[52:53], v[0:1] op_sel_hi:[1,0]
	v_pk_mul_f32 v[54:55], v[14:15], v[0:1] op_sel_hi:[1,0]
	v_pk_mul_f32 v[50:51], v[50:51], v[0:1] op_sel_hi:[1,0]
	v_pk_mul_f32 v[58:59], v[62:63], v[0:1] op_sel_hi:[1,0]
	v_pk_mul_f32 v[56:57], v[56:57], v[0:1] op_sel_hi:[1,0]
	v_pk_mul_f32 v[48:49], v[48:49], v[0:1] op_sel_hi:[1,0]
	s_waitcnt vmcnt(5)
	v_pk_fma_f32 v[16:17], v[4:5], v[16:17], v[12:13]
	v_pk_fma_f32 v[14:15], v[2:3], v[46:47], v[10:11]
	s_waitcnt vmcnt(4)
	v_pk_fma_f32 v[12:13], v[8:9], v[54:55], v[28:29]
	v_pk_fma_f32 v[10:11], v[6:7], v[52:53], v[26:27]
	s_waitcnt vmcnt(1)
	v_pk_fma_f32 v[8:9], v[32:33], v[58:59], v[40:41]
	v_pk_fma_f32 v[6:7], v[30:31], v[50:51], v[38:39]
	s_waitcnt vmcnt(0)
	v_pk_fma_f32 v[4:5], v[36:37], v[48:49], v[44:45]
	v_pk_fma_f32 v[2:3], v[34:35], v[56:57], v[42:43]
	v_mov_b32_e32 v26, 1.0
	v_mov_b32_e32 v28, v132
	v_mov_b32_e32 v29, v133
	v_mov_b32_e32 v27, v26
	s_waitcnt vmcnt(3)
	global_store_dwordx4 v[130:131], v[14:17], off offset:-3072 nt
	v_mov_b32_e32 v30, v26
	v_mov_b32_e32 v31, v26
	v_pk_mul_f32 v[16:17], v[16:17], v[30:31]
	v_pk_mul_f32 v[14:15], v[14:15], v[26:27]
	s_nop 0
	v_cvt_pk_bf16_f32 v14, v14, v15
	v_cvt_pk_bf16_f32 v15, v16, v17
	v_add_co_u32_e32 v16, vcc, 0x2b00000, v28
	s_nop 1
	v_addc_co_u32_e32 v17, vcc, 0, v29, vcc
	global_store_dwordx2 v[16:17], v[14:15], off
	s_waitcnt vmcnt(4)
	global_store_dwordx4 v[130:131], v[10:13], off offset:-2048 nt
	v_pk_mul_f32 v[14:15], v[12:13], v[30:31]
	v_pk_mul_f32 v[30:31], v[10:11], v[26:27]
	s_nop 0
	v_cvt_pk_bf16_f32 v30, v30, v31
	v_cvt_pk_bf16_f32 v31, v14, v15
	global_store_dwordx2 v[16:17], v[30:31], off offset:512
	s_waitcnt vmcnt(2)
	global_store_dwordx4 v[130:131], v[6:9], off offset:-1024 nt
	v_mov_b32_e32 v10, v26
	v_mov_b32_e32 v11, v26
	v_pk_mul_f32 v[8:9], v[8:9], v[10:11]
	v_pk_mul_f32 v[6:7], v[6:7], v[26:27]
	s_nop 0
	v_cvt_pk_bf16_f32 v6, v6, v7
	v_cvt_pk_bf16_f32 v7, v8, v9
	v_add_co_u32_e32 v8, vcc, 0x2b00000, v28
	s_nop 1
	v_addc_co_u32_e32 v9, vcc, 0, v29, vcc
	global_store_dwordx2 v[8:9], v[6:7], off offset:1024
	s_waitcnt vmcnt(3)
	global_store_dwordx4 v[130:131], v[2:5], off nt
	v_pk_mul_f32 v[6:7], v[4:5], v[10:11]
	v_pk_mul_f32 v[10:11], v[2:3], v[26:27]
	s_nop 0
	v_cvt_pk_bf16_f32 v10, v10, v11
	v_cvt_pk_bf16_f32 v11, v6, v7
	global_store_dwordx2 v[8:9], v[10:11], off offset:1536
	v_cvt_pk_bf16_f32 v142, v142, v143
	v_cvt_pk_bf16_f32 v143, v144, v145
	global_store_dwordx2 v[150:151], v[142:143], off
	s_branch .LBB0_150
.Lrq_tail2:
	s_waitcnt vmcnt(0)
	s_waitcnt vmcnt(11)
	v_and_b32_e32 v117, 0xffff0000, v78
	v_lshlrev_b32_e32 v115, 16, v78
	s_waitcnt vmcnt(9)
	v_and_b32_e32 v116, 0xffff0000, v110
	v_lshlrev_b32_e32 v114, 16, v110
	v_lshlrev_b32_e32 v118, 16, v111
	v_and_b32_e32 v78, 0xffff0000, v111
	s_waitcnt vmcnt(8)
	v_lshlrev_b32_e32 v111, 16, v112
	v_lshlrev_b32_e32 v110, 16, v80
	v_and_b32_e32 v121, 0xffff0000, v112
	v_and_b32_e32 v120, 0xffff0000, v80
	v_lshlrev_b32_e32 v122, 16, v81
	v_and_b32_e32 v112, 0xffff0000, v81
	v_pk_mul_f32 v[80:81], v[116:117], v[116:117]
	v_lshlrev_b32_e32 v119, 16, v79
	v_pk_mul_f32 v[124:125], v[120:121], v[120:121]
	v_pk_fma_f32 v[80:81], v[114:115], v[114:115], v[80:81]
	v_and_b32_e32 v79, 0xffff0000, v79
	v_lshlrev_b32_e32 v123, 16, v113
	v_pk_fma_f32 v[124:125], v[110:111], v[110:111], v[124:125]
	v_pk_fma_f32 v[80:81], v[118:119], v[118:119], v[80:81]
	v_and_b32_e32 v113, 0xffff0000, v113
	v_pk_fma_f32 v[124:125], v[122:123], v[122:123], v[124:125]
	v_pk_fma_f32 v[80:81], v[78:79], v[78:79], v[80:81]
	v_pk_fma_f32 v[124:125], v[112:113], v[112:113], v[124:125]
	v_add_f32_e32 v64, v80, v81
	v_add_f32_e32 v64, v64, v124
	v_add_f32_e32 v64, v64, v125
	ds_bpermute_b32 v80, v163, v64
	v_mov_b32_e32 v125, v78
	v_mov_b32_e32 v124, v118
	v_mov_b32_e32 v126, v122
	v_mov_b32_e32 v127, v112
	s_waitcnt lgkmcnt(0)
	v_add_f32_e32 v64, v64, v80
	ds_bpermute_b32 v80, v164, v64
	v_mov_b32_e32 v112, v123
	s_waitcnt lgkmcnt(0)
	v_add_f32_e32 v64, v64, v80
	ds_bpermute_b32 v80, v165, v64
	s_waitcnt lgkmcnt(0)
	v_add_f32_e32 v64, v64, v80
	ds_bpermute_b32 v81, v166, v64
	v_mov_b32_e32 v80, v114
	s_waitcnt lgkmcnt(0)
	v_add_f32_e32 v64, v64, v81
	ds_bpermute_b32 v114, v167, v64
	v_mov_b32_e32 v81, v116
	v_mov_b32_e32 v116, v115
	v_mov_b32_e32 v115, v120
	v_mov_b32_e32 v120, v111
	s_waitcnt lgkmcnt(0)
	v_add_f32_e32 v64, v64, v114
	ds_bpermute_b32 v78, v168, v64
	v_mov_b32_e32 v114, v110
	s_waitcnt lgkmcnt(0)
	v_add_f32_e32 v64, v64, v78
	v_fmamk_f32 v64, v64, 0x3a800000, v169
	v_mul_f32_e32 v78, 0x4b800000, v64
	v_cmp_gt_f32_e32 vcc, s74, v64
	s_nop 1
	v_cndmask_b32_e32 v64, v64, v78, vcc
	v_rsq_f32_e32 v64, v64
	v_mov_b32_e32 v78, v119
	v_mul_f32_e32 v110, 0x45800000, v64
	v_cndmask_b32_e32 v64, v64, v110, vcc
	v_pk_mul_f32 v[110:111], v[80:81], v[64:65] op_sel_hi:[1,0]
	v_pk_mul_f32 v[80:81], v[124:125], v[64:65] op_sel_hi:[1,0]
	v_pk_mul_f32 v[116:117], v[116:117], v[64:65] op_sel_hi:[1,0]
	v_pk_mul_f32 v[118:119], v[78:79], v[64:65] op_sel_hi:[1,0]
	v_pk_mul_f32 v[114:115], v[114:115], v[64:65] op_sel_hi:[1,0]
	v_pk_mul_f32 v[122:123], v[126:127], v[64:65] op_sel_hi:[1,0]
	v_pk_mul_f32 v[120:121], v[120:121], v[64:65] op_sel_hi:[1,0]
	v_pk_mul_f32 v[112:113], v[112:113], v[64:65] op_sel_hi:[1,0]
	s_waitcnt vmcnt(5)
	v_pk_fma_f32 v[80:81], v[68:69], v[80:81], v[76:77]
	v_pk_fma_f32 v[78:79], v[66:67], v[110:111], v[74:75]
	s_waitcnt vmcnt(4)
	v_pk_fma_f32 v[76:77], v[72:73], v[118:119], v[92:93]
	v_pk_fma_f32 v[74:75], v[70:71], v[116:117], v[90:91]
	s_waitcnt vmcnt(1)
	v_pk_fma_f32 v[72:73], v[96:97], v[122:123], v[104:105]
	v_pk_fma_f32 v[70:71], v[94:95], v[114:115], v[102:103]
	s_waitcnt vmcnt(0)
	v_pk_fma_f32 v[68:69], v[100:101], v[112:113], v[108:109]
	v_pk_fma_f32 v[66:67], v[98:99], v[120:121], v[106:107]
	v_mov_b32_e32 v90, 1.0
	v_mov_b32_e32 v92, v136
	v_mov_b32_e32 v93, v137
	v_mov_b32_e32 v91, v90
	s_waitcnt vmcnt(3)
	global_store_dwordx4 v[134:135], v[78:81], off offset:-3072 nt
	v_mov_b32_e32 v94, v90
	v_mov_b32_e32 v95, v90
	v_pk_mul_f32 v[80:81], v[80:81], v[94:95]
	v_pk_mul_f32 v[78:79], v[78:79], v[90:91]
	s_nop 0
	v_cvt_pk_bf16_f32 v78, v78, v79
	v_cvt_pk_bf16_f32 v79, v80, v81
	v_add_co_u32_e32 v80, vcc, 0x2b00000, v92
	s_nop 1
	v_addc_co_u32_e32 v81, vcc, 0, v93, vcc
	global_store_dwordx2 v[80:81], v[78:79], off
	s_waitcnt vmcnt(4)
	global_store_dwordx4 v[134:135], v[74:77], off offset:-2048 nt
	v_pk_mul_f32 v[78:79], v[76:77], v[94:95]
	v_pk_mul_f32 v[94:95], v[74:75], v[90:91]
	s_nop 0
	v_cvt_pk_bf16_f32 v94, v94, v95
	v_cvt_pk_bf16_f32 v95, v78, v79
	global_store_dwordx2 v[80:81], v[94:95], off offset:512
	s_waitcnt vmcnt(2)
	global_store_dwordx4 v[134:135], v[70:73], off offset:-1024 nt
	v_mov_b32_e32 v74, v90
	v_mov_b32_e32 v75, v90
	v_pk_mul_f32 v[72:73], v[72:73], v[74:75]
	v_pk_mul_f32 v[70:71], v[70:71], v[90:91]
	s_nop 0
	v_cvt_pk_bf16_f32 v70, v70, v71
	v_cvt_pk_bf16_f32 v71, v72, v73
	v_add_co_u32_e32 v72, vcc, 0x2b00000, v92
	s_nop 1
	v_addc_co_u32_e32 v73, vcc, 0, v93, vcc
	global_store_dwordx2 v[72:73], v[70:71], off offset:1024
	s_waitcnt vmcnt(3)
	global_store_dwordx4 v[134:135], v[66:69], off nt
	v_pk_mul_f32 v[70:71], v[68:69], v[74:75]
	v_pk_mul_f32 v[74:75], v[66:67], v[90:91]
	s_nop 0
	v_cvt_pk_bf16_f32 v74, v74, v75
	v_cvt_pk_bf16_f32 v75, v70, v71
	global_store_dwordx2 v[72:73], v[74:75], off offset:1536
	v_cvt_pk_bf16_f32 v146, v146, v147
	v_cvt_pk_bf16_f32 v147, v148, v149
	global_store_dwordx2 v[152:153], v[146:147], off
	s_branch .LBB0_150
